# HGRN state update: decay of tile kt+1 issued ahead of tile kt's MFMA (no s_nop pads) (v60 + m5pipe)
# baseline (speedup 1.0000x reference)
.LBB0_950:
	v_lshlrev_b32_e32 v0, 1, v135
	v_lshlrev_b32_e32 v1, 1, v154
	v_add3_u32 v2, s62, v0, v1
	v_add_u32_e32 v207, s62, v63
	v_lshl_add_u32 v227, v54, 1, v207
	v_add_u32_e32 v0, v2, v176
	ds_read_b128 v[36:39], v2 offset:4352
	ds_read_b128 v[40:43], v2
	ds_read_b128 v[208:211], v2 offset:4416
	ds_read_b128 v[184:187], v2 offset:64
	ds_read_b128 v[212:215], v2 offset:4480
	ds_read_b128 v[228:231], v2 offset:128
	ds_read_b128 v[232:235], v2 offset:4544
	ds_read_b128 v[236:239], v2 offset:192
	ds_read_b64 v[188:189], v227 offset:14848
	ds_read2_b64 v[240:243], v0 offset1:4
	ds_read2_b64 v[244:247], v0 offset0:8 offset1:12
	s_and_b64 s[12:13], s[54:55], s[52:53]
	v_mov_b32_e32 v190, v3
	v_mov_b32_e32 v191, v3
	s_waitcnt lgkmcnt(9)
	v_mfma_f32_16x16x32_bf16 v[36:39], v[36:39], v[40:43], 0
	s_waitcnt lgkmcnt(7)
	v_mfma_f32_16x16x32_bf16 v[36:39], v[208:211], v[184:187], v[36:39]
	s_waitcnt lgkmcnt(5)
	v_mfma_f32_16x16x32_bf16 v[36:39], v[212:215], v[228:231], v[36:39]
	s_waitcnt lgkmcnt(3)
	v_mfma_f32_16x16x32_bf16 v[36:39], v[232:235], v[236:239], v[36:39]
	ds_read2_b64 v[208:211], v0 offset0:16 offset1:20
	ds_read2_b64 v[212:215], v0 offset0:24 offset1:28
	v_cvt_pk_bf16_f32 v184, v4, v5
	v_cvt_pk_bf16_f32 v185, v6, v7
	v_cvt_pk_bf16_f32 v186, v8, v9
	v_cvt_pk_bf16_f32 v187, v10, v11
	v_mov_b32_e32 v2, v3
	s_nop 0
	v_cndmask_b32_e64 v192, v38, 0, s[12:13]
	s_and_b64 s[12:13], s[12:13], s[50:51]
	v_cndmask_b32_e64 v0, v37, 0, s[12:13]
	s_and_b64 s[12:13], s[12:13], s[48:49]
	v_cndmask_b32_e64 v36, v36, 0, s[12:13]
	v_cndmask_b32_e64 v1, v39, 0, s[54:55]
	v_cvt_pk_bf16_f32 v0, v36, v0
	v_cvt_pk_bf16_f32 v1, v192, v1
	s_nop 0
	s_waitcnt lgkmcnt(4)
	v_mfma_f32_16x16x32_bf16 v[36:39], v[188:191], v[0:3], 0
	v_cvt_pk_bf16_f32 v40, v12, v13
	v_cvt_pk_bf16_f32 v41, v14, v15
	v_cvt_pk_bf16_f32 v42, v16, v17
	v_cvt_pk_bf16_f32 v43, v18, v19
	v_cvt_pk_bf16_f32 v228, v20, v21
	v_cvt_pk_bf16_f32 v229, v22, v23
	v_cvt_pk_bf16_f32 v230, v24, v25
	v_cvt_pk_bf16_f32 v231, v26, v27
	v_cvt_pk_bf16_f32 v232, v28, v29
	v_cvt_pk_bf16_f32 v233, v30, v31
	v_cvt_pk_bf16_f32 v234, v32, v33
	v_cvt_pk_bf16_f32 v235, v34, v35
	s_waitcnt lgkmcnt(3)
	v_mfma_f32_16x16x32_bf16 v[36:39], v[184:187], v[240:243], v[36:39]
	s_waitcnt lgkmcnt(2)
	v_mfma_f32_16x16x32_bf16 v[36:39], v[40:43], v[244:247], v[36:39]
	s_waitcnt lgkmcnt(1)
	v_mfma_f32_16x16x32_bf16 v[36:39], v[228:231], v[208:211], v[36:39]
	s_waitcnt lgkmcnt(0)
	v_mfma_f32_16x16x32_bf16 v[36:39], v[232:235], v[212:215], v[36:39]
	v_add_u32_e32 v227, v207, v155
	v_add_u32_e32 v216, s62, v142
	v_add3_u32 v217, s62, v155, v156
	v_mov_b32_e32 v32, 0
	v_mov_b32_e32 v33, 0
	v_mov_b32_e32 v34, 0
	v_mov_b32_e32 v35, 0
	s_and_saveexec_b64 s[12:13], s[46:47]
	ds_read_b128 v[32:35], v227 offset:14848
	s_or_b64 exec, exec, s[12:13]
	ds_read_b64 v[240:241], v216 offset:20992
	ds_read_b128 v[184:187], v217 offset:8704
	ds_read_b128 v[40:43], v217 offset:9472
	ds_read_b128 v[228:231], v217 offset:10240
	ds_read_b128 v[232:235], v217 offset:11008
	s_ashr_i32 s12, s32, 4
	s_add_i32 s12, s12, -2
	v_sub_u32_e32 v0, v51, v54
	v_cvt_pk_bf16_f32 v192, v36, v37
	v_cvt_pk_bf16_f32 v193, v38, v39
	v_mad_i32_i24 v0, v0, s12, v197
	global_store_dwordx2 v0, v[192:193], s[100:101]
	s_waitcnt lgkmcnt(4)
	v_mul_f32_dpp v4, v240, v4 row_newbcast:0 row_mask:0xf bank_mask:0xf
	v_mul_f32_dpp v5, v241, v5 row_newbcast:0 row_mask:0xf bank_mask:0xf
	v_mul_f32_dpp v6, v240, v6 row_newbcast:1 row_mask:0xf bank_mask:0xf
	v_mul_f32_dpp v7, v241, v7 row_newbcast:1 row_mask:0xf bank_mask:0xf
	v_mul_f32_dpp v8, v240, v8 row_newbcast:2 row_mask:0xf bank_mask:0xf
	v_mul_f32_dpp v9, v241, v9 row_newbcast:2 row_mask:0xf bank_mask:0xf
	v_mul_f32_dpp v10, v240, v10 row_newbcast:3 row_mask:0xf bank_mask:0xf
	v_mul_f32_dpp v11, v241, v11 row_newbcast:3 row_mask:0xf bank_mask:0xf
	s_waitcnt lgkmcnt(3)
	v_mfma_f32_16x16x32_bf16 v[4:7], v[184:187], v[32:35], v[4:7]
	ds_read_b128 v[184:187], v217 offset:11776
	v_mul_f32_dpp v12, v240, v12 row_newbcast:4 row_mask:0xf bank_mask:0xf
	v_mul_f32_dpp v13, v241, v13 row_newbcast:4 row_mask:0xf bank_mask:0xf
	v_mul_f32_dpp v14, v240, v14 row_newbcast:5 row_mask:0xf bank_mask:0xf
	v_mul_f32_dpp v15, v241, v15 row_newbcast:5 row_mask:0xf bank_mask:0xf
	s_waitcnt lgkmcnt(3)
	v_mfma_f32_16x16x32_bf16 v[8:11], v[40:43], v[32:35], v[8:11]
	ds_read_b128 v[40:43], v217 offset:12544
	v_mul_f32_dpp v16, v240, v16 row_newbcast:6 row_mask:0xf bank_mask:0xf
	v_mul_f32_dpp v17, v241, v17 row_newbcast:6 row_mask:0xf bank_mask:0xf
	v_mul_f32_dpp v18, v240, v18 row_newbcast:7 row_mask:0xf bank_mask:0xf
	v_mul_f32_dpp v19, v241, v19 row_newbcast:7 row_mask:0xf bank_mask:0xf
	s_waitcnt lgkmcnt(3)
	v_mfma_f32_16x16x32_bf16 v[12:15], v[228:231], v[32:35], v[12:15]
	ds_read_b128 v[228:231], v217 offset:13312
	v_mul_f32_dpp v20, v240, v20 row_newbcast:8 row_mask:0xf bank_mask:0xf
	v_mul_f32_dpp v21, v241, v21 row_newbcast:8 row_mask:0xf bank_mask:0xf
	v_mul_f32_dpp v22, v240, v22 row_newbcast:9 row_mask:0xf bank_mask:0xf
	v_mul_f32_dpp v23, v241, v23 row_newbcast:9 row_mask:0xf bank_mask:0xf
	s_waitcnt lgkmcnt(3)
	v_mfma_f32_16x16x32_bf16 v[16:19], v[232:235], v[32:35], v[16:19]
	ds_read_b128 v[232:235], v217 offset:14080
	v_mul_f32_dpp v24, v240, v24 row_newbcast:10 row_mask:0xf bank_mask:0xf
	v_mul_f32_dpp v25, v241, v25 row_newbcast:10 row_mask:0xf bank_mask:0xf
	v_mul_f32_dpp v26, v240, v26 row_newbcast:11 row_mask:0xf bank_mask:0xf
	v_mul_f32_dpp v27, v241, v27 row_newbcast:11 row_mask:0xf bank_mask:0xf
	s_waitcnt lgkmcnt(3)
	v_mfma_f32_16x16x32_bf16 v[20:23], v[184:187], v[32:35], v[20:23]
	v_mul_f32_dpp v28, v240, v28 row_newbcast:12 row_mask:0xf bank_mask:0xf
	v_mul_f32_dpp v29, v241, v29 row_newbcast:12 row_mask:0xf bank_mask:0xf
	v_mul_f32_dpp v30, v240, v30 row_newbcast:13 row_mask:0xf bank_mask:0xf
	v_mul_f32_dpp v31, v241, v31 row_newbcast:13 row_mask:0xf bank_mask:0xf
	s_waitcnt lgkmcnt(2)
	v_mfma_f32_16x16x32_bf16 v[24:27], v[40:43], v[32:35], v[24:27]
	v_mul_f32_dpp v212, v240, v148 row_newbcast:14 row_mask:0xf bank_mask:0xf
	v_mul_f32_dpp v213, v241, v149 row_newbcast:14 row_mask:0xf bank_mask:0xf
	v_mul_f32_dpp v214, v240, v150 row_newbcast:15 row_mask:0xf bank_mask:0xf
	v_mul_f32_dpp v215, v241, v151 row_newbcast:15 row_mask:0xf bank_mask:0xf
	s_waitcnt lgkmcnt(1)
	v_mfma_f32_16x16x32_bf16 v[28:31], v[228:231], v[32:35], v[28:31]
	s_waitcnt lgkmcnt(0)
	s_nop 0
	v_mfma_f32_16x16x32_bf16 v[32:35], v[232:235], v[32:35], v[212:215]
	v_add_u32_e32 v197, s32, v197
	v_add_u32_e32 v198, s32, v198
	v_add_u32_e32 v248, s32, v248
	v_add_u32_e32 v249, s32, v249
	v_lshl_add_u64 v[48:49], v[48:49], 0, v[46:47]
	s_add_i32 s60, s60, 16
	s_add_i32 s61, s61, 1
	s_cmpk_lg_i32 s60, 0x100
	s_barrier
	s_cbranch_scc1 .LBB0_943
	s_mov_b64 s[58:59], -1
	s_branch .LBB0_1005
.Lhc_alt_top:
	s_nop 2
	v_mov_b32_e32 v148, v32
	v_mov_b32_e32 v149, v33
	v_mov_b32_e32 v150, v34
	v_mov_b32_e32 v151, v35
	s_bitcmp1_b32 s61, 0
	s_cselect_b32 s62, 0x5800, 0
	v_lshlrev_b32_e32 v0, 1, v135
	v_lshlrev_b32_e32 v1, 1, v154
	v_add3_u32 v2, s62, v0, v1
	v_add_u32_e32 v207, s62, v63
	v_lshl_add_u32 v227, v54, 1, v207
	v_add_u32_e32 v0, v2, v176
	ds_read_b128 v[36:39], v2 offset:4352
	ds_read_b128 v[40:43], v2
	ds_read_b128 v[208:211], v2 offset:4416
	ds_read_b128 v[184:187], v2 offset:64
	ds_read_b128 v[212:215], v2 offset:4480
	ds_read_b128 v[228:231], v2 offset:128
	ds_read_b128 v[232:235], v2 offset:4544
	ds_read_b128 v[236:239], v2 offset:192
	ds_read_b64 v[188:189], v227 offset:14848
	ds_read2_b64 v[240:243], v0 offset1:4
	ds_read2_b64 v[244:247], v0 offset0:8 offset1:12
	s_and_b64 s[12:13], s[54:55], s[52:53]
	v_mov_b32_e32 v190, v3
	v_mov_b32_e32 v191, v3
	s_waitcnt lgkmcnt(9)
	v_mfma_f32_16x16x32_bf16 v[36:39], v[36:39], v[40:43], 0
	s_waitcnt lgkmcnt(7)
	v_mfma_f32_16x16x32_bf16 v[36:39], v[208:211], v[184:187], v[36:39]
	s_waitcnt lgkmcnt(5)
	v_mfma_f32_16x16x32_bf16 v[36:39], v[212:215], v[228:231], v[36:39]
	s_waitcnt lgkmcnt(3)
	v_mfma_f32_16x16x32_bf16 v[36:39], v[232:235], v[236:239], v[36:39]
	ds_read2_b64 v[208:211], v0 offset0:16 offset1:20
	ds_read2_b64 v[212:215], v0 offset0:24 offset1:28
	v_cvt_pk_bf16_f32 v184, v4, v5
	v_cvt_pk_bf16_f32 v185, v6, v7
	v_cvt_pk_bf16_f32 v186, v8, v9
	v_cvt_pk_bf16_f32 v187, v10, v11
	v_mov_b32_e32 v2, v3
	s_nop 0
	v_cndmask_b32_e64 v192, v38, 0, s[12:13]
	s_and_b64 s[12:13], s[12:13], s[50:51]
	v_cndmask_b32_e64 v0, v37, 0, s[12:13]
	s_and_b64 s[12:13], s[12:13], s[48:49]
	v_cndmask_b32_e64 v36, v36, 0, s[12:13]
	v_cndmask_b32_e64 v1, v39, 0, s[54:55]
	v_cvt_pk_bf16_f32 v0, v36, v0
	v_cvt_pk_bf16_f32 v1, v192, v1
	s_nop 0
	s_waitcnt lgkmcnt(4)
	v_mfma_f32_16x16x32_bf16 v[36:39], v[188:191], v[0:3], 0
	v_cvt_pk_bf16_f32 v40, v12, v13
	v_cvt_pk_bf16_f32 v41, v14, v15
	v_cvt_pk_bf16_f32 v42, v16, v17
	v_cvt_pk_bf16_f32 v43, v18, v19
	v_cvt_pk_bf16_f32 v228, v20, v21
	v_cvt_pk_bf16_f32 v229, v22, v23
	v_cvt_pk_bf16_f32 v230, v24, v25
	v_cvt_pk_bf16_f32 v231, v26, v27
	v_cvt_pk_bf16_f32 v232, v28, v29
	v_cvt_pk_bf16_f32 v233, v30, v31
	v_cvt_pk_bf16_f32 v234, v32, v33
	v_cvt_pk_bf16_f32 v235, v34, v35
	s_waitcnt lgkmcnt(3)
	v_mfma_f32_16x16x32_bf16 v[36:39], v[184:187], v[240:243], v[36:39]
	s_waitcnt lgkmcnt(2)
	v_mfma_f32_16x16x32_bf16 v[36:39], v[40:43], v[244:247], v[36:39]
	s_waitcnt lgkmcnt(1)
	v_mfma_f32_16x16x32_bf16 v[36:39], v[228:231], v[208:211], v[36:39]
	s_waitcnt lgkmcnt(0)
	v_mfma_f32_16x16x32_bf16 v[36:39], v[232:235], v[212:215], v[36:39]
	v_add_u32_e32 v227, v207, v155
	v_add_u32_e32 v216, s62, v142
	v_add3_u32 v217, s62, v155, v156
	v_mov_b32_e32 v32, 0
	v_mov_b32_e32 v33, 0
	v_mov_b32_e32 v34, 0
	v_mov_b32_e32 v35, 0
	s_and_saveexec_b64 s[12:13], s[46:47]
	ds_read_b128 v[32:35], v227 offset:14848
	s_or_b64 exec, exec, s[12:13]
	ds_read_b64 v[240:241], v216 offset:20992
	ds_read_b128 v[184:187], v217 offset:8704
	ds_read_b128 v[40:43], v217 offset:9472
	ds_read_b128 v[228:231], v217 offset:10240
	ds_read_b128 v[232:235], v217 offset:11008
	s_ashr_i32 s12, s32, 4
	s_add_i32 s12, s12, -2
	v_sub_u32_e32 v0, v51, v54
	v_cvt_pk_bf16_f32 v192, v36, v37
	v_cvt_pk_bf16_f32 v193, v38, v39
	v_mad_i32_i24 v0, v0, s12, v197
	global_store_dwordx2 v0, v[192:193], s[100:101]
	s_waitcnt lgkmcnt(4)
	v_mul_f32_dpp v4, v240, v4 row_newbcast:0 row_mask:0xf bank_mask:0xf
	v_mul_f32_dpp v5, v241, v5 row_newbcast:0 row_mask:0xf bank_mask:0xf
	v_mul_f32_dpp v6, v240, v6 row_newbcast:1 row_mask:0xf bank_mask:0xf
	v_mul_f32_dpp v7, v241, v7 row_newbcast:1 row_mask:0xf bank_mask:0xf
	v_mul_f32_dpp v8, v240, v8 row_newbcast:2 row_mask:0xf bank_mask:0xf
	v_mul_f32_dpp v9, v241, v9 row_newbcast:2 row_mask:0xf bank_mask:0xf
	v_mul_f32_dpp v10, v240, v10 row_newbcast:3 row_mask:0xf bank_mask:0xf
	v_mul_f32_dpp v11, v241, v11 row_newbcast:3 row_mask:0xf bank_mask:0xf
	s_waitcnt lgkmcnt(3)
	v_mfma_f32_16x16x32_bf16 v[4:7], v[184:187], v[32:35], v[4:7]
	ds_read_b128 v[184:187], v217 offset:11776
	v_mul_f32_dpp v12, v240, v12 row_newbcast:4 row_mask:0xf bank_mask:0xf
	v_mul_f32_dpp v13, v241, v13 row_newbcast:4 row_mask:0xf bank_mask:0xf
	v_mul_f32_dpp v14, v240, v14 row_newbcast:5 row_mask:0xf bank_mask:0xf
	v_mul_f32_dpp v15, v241, v15 row_newbcast:5 row_mask:0xf bank_mask:0xf
	s_waitcnt lgkmcnt(3)
	v_mfma_f32_16x16x32_bf16 v[8:11], v[40:43], v[32:35], v[8:11]
	ds_read_b128 v[40:43], v217 offset:12544
	v_mul_f32_dpp v16, v240, v16 row_newbcast:6 row_mask:0xf bank_mask:0xf
	v_mul_f32_dpp v17, v241, v17 row_newbcast:6 row_mask:0xf bank_mask:0xf
	v_mul_f32_dpp v18, v240, v18 row_newbcast:7 row_mask:0xf bank_mask:0xf
	v_mul_f32_dpp v19, v241, v19 row_newbcast:7 row_mask:0xf bank_mask:0xf
	s_waitcnt lgkmcnt(3)
	v_mfma_f32_16x16x32_bf16 v[12:15], v[228:231], v[32:35], v[12:15]
	ds_read_b128 v[228:231], v217 offset:13312
	v_mul_f32_dpp v20, v240, v20 row_newbcast:8 row_mask:0xf bank_mask:0xf
	v_mul_f32_dpp v21, v241, v21 row_newbcast:8 row_mask:0xf bank_mask:0xf
	v_mul_f32_dpp v22, v240, v22 row_newbcast:9 row_mask:0xf bank_mask:0xf
	v_mul_f32_dpp v23, v241, v23 row_newbcast:9 row_mask:0xf bank_mask:0xf
	s_waitcnt lgkmcnt(3)
	v_mfma_f32_16x16x32_bf16 v[16:19], v[232:235], v[32:35], v[16:19]
	ds_read_b128 v[232:235], v217 offset:14080
	v_mul_f32_dpp v24, v240, v24 row_newbcast:10 row_mask:0xf bank_mask:0xf
	v_mul_f32_dpp v25, v241, v25 row_newbcast:10 row_mask:0xf bank_mask:0xf
	v_mul_f32_dpp v26, v240, v26 row_newbcast:11 row_mask:0xf bank_mask:0xf
	v_mul_f32_dpp v27, v241, v27 row_newbcast:11 row_mask:0xf bank_mask:0xf
	s_waitcnt lgkmcnt(3)
	v_mfma_f32_16x16x32_bf16 v[20:23], v[184:187], v[32:35], v[20:23]
	v_mul_f32_dpp v28, v240, v28 row_newbcast:12 row_mask:0xf bank_mask:0xf
	v_mul_f32_dpp v29, v241, v29 row_newbcast:12 row_mask:0xf bank_mask:0xf
	v_mul_f32_dpp v30, v240, v30 row_newbcast:13 row_mask:0xf bank_mask:0xf
	v_mul_f32_dpp v31, v241, v31 row_newbcast:13 row_mask:0xf bank_mask:0xf
	s_waitcnt lgkmcnt(2)
	v_mfma_f32_16x16x32_bf16 v[24:27], v[40:43], v[32:35], v[24:27]
	v_mul_f32_dpp v212, v240, v148 row_newbcast:14 row_mask:0xf bank_mask:0xf
	v_mul_f32_dpp v213, v241, v149 row_newbcast:14 row_mask:0xf bank_mask:0xf
	v_mul_f32_dpp v214, v240, v150 row_newbcast:15 row_mask:0xf bank_mask:0xf
	v_mul_f32_dpp v215, v241, v151 row_newbcast:15 row_mask:0xf bank_mask:0xf
	s_waitcnt lgkmcnt(1)
	v_mfma_f32_16x16x32_bf16 v[28:31], v[228:231], v[32:35], v[28:31]
	s_waitcnt lgkmcnt(0)
	s_nop 0
	v_mfma_f32_16x16x32_bf16 v[32:35], v[232:235], v[32:35], v[212:215]
	s_cmp_gt_u32 s61, 14
	s_cbranch_scc1 .Lhc_alt_tail
	s_waitcnt vmcnt(1)
	v_mov_b32_e32 v44, v200
	v_mov_b32_e32 v42, v202
	v_mov_b32_e32 v40, v204
	v_mov_b32_e32 v38, v206
	v_mov_b32_e32 v45, v199
	v_mov_b32_e32 v43, v201
	v_mov_b32_e32 v41, v203
	v_mov_b32_e32 v39, v205
	v_mov_b64_e32 v[36:37], v[152:153]
	s_cmpk_eq_i32 s60, 0xe0
	s_cbranch_scc1 .Lhc_alt_947
	global_load_ushort v199, v197, s[24:25]
	global_load_ushort v200, v197, s[98:99]
	global_load_ushort v201, v198, s[24:25]
	global_load_ushort v202, v198, s[98:99]
	global_load_ushort v203, v248, s[24:25]
	global_load_ushort v204, v248, s[98:99]
	global_load_ushort v205, v249, s[24:25]
	global_load_ushort v206, v249, s[98:99]
	global_load_dwordx2 v[152:153], v[48:49], off

.LBB0_985:
	v_lshlrev_b32_e32 v0, 1, v135
	v_lshlrev_b32_e32 v1, 1, v154
	v_add3_u32 v2, s82, v0, v1
	v_add_u32_e32 v207, s82, v63
	v_lshl_add_u32 v227, v54, 1, v207
	v_add_u32_e32 v0, v2, v176
	ds_read_b128 v[36:39], v2 offset:4352
	ds_read_b128 v[40:43], v2
	ds_read_b128 v[208:211], v2 offset:4416
	ds_read_b128 v[184:187], v2 offset:64
	ds_read_b128 v[212:215], v2 offset:4480
	ds_read_b128 v[228:231], v2 offset:128
	ds_read_b128 v[232:235], v2 offset:4544
	ds_read_b128 v[236:239], v2 offset:192
	ds_read_b64 v[188:189], v227 offset:14848
	ds_read2_b64 v[240:243], v0 offset1:4
	ds_read2_b64 v[244:247], v0 offset0:8 offset1:12
	s_and_b64 s[14:15], s[54:55], s[52:53]
	v_mov_b32_e32 v190, v3
	v_mov_b32_e32 v191, v3
	s_waitcnt lgkmcnt(9)
	v_mfma_f32_16x16x32_bf16 v[36:39], v[36:39], v[40:43], 0
	s_waitcnt lgkmcnt(7)
	v_mfma_f32_16x16x32_bf16 v[36:39], v[208:211], v[184:187], v[36:39]
	s_waitcnt lgkmcnt(5)
	v_mfma_f32_16x16x32_bf16 v[36:39], v[212:215], v[228:231], v[36:39]
	s_waitcnt lgkmcnt(3)
	v_mfma_f32_16x16x32_bf16 v[36:39], v[232:235], v[236:239], v[36:39]
	ds_read2_b64 v[208:211], v0 offset0:16 offset1:20
	ds_read2_b64 v[212:215], v0 offset0:24 offset1:28
	v_cvt_pk_bf16_f32 v184, v4, v5
	v_cvt_pk_bf16_f32 v185, v6, v7
	v_cvt_pk_bf16_f32 v186, v8, v9
	v_cvt_pk_bf16_f32 v187, v10, v11
	v_mov_b32_e32 v2, v3
	s_nop 0
	v_cndmask_b32_e64 v192, v38, 0, s[14:15]
	s_and_b64 s[14:15], s[14:15], s[50:51]
	v_cndmask_b32_e64 v0, v37, 0, s[14:15]
	s_and_b64 s[14:15], s[14:15], s[48:49]
	v_cndmask_b32_e64 v36, v36, 0, s[14:15]
	v_cndmask_b32_e64 v1, v39, 0, s[54:55]
	v_cvt_pk_bf16_f32 v0, v36, v0
	v_cvt_pk_bf16_f32 v1, v192, v1
	s_nop 0
	s_waitcnt lgkmcnt(4)
	v_mfma_f32_16x16x32_bf16 v[36:39], v[188:191], v[0:3], 0
	v_cvt_pk_bf16_f32 v40, v12, v13
	v_cvt_pk_bf16_f32 v41, v14, v15
	v_cvt_pk_bf16_f32 v42, v16, v17
	v_cvt_pk_bf16_f32 v43, v18, v19
	v_cvt_pk_bf16_f32 v228, v20, v21
	v_cvt_pk_bf16_f32 v229, v22, v23
	v_cvt_pk_bf16_f32 v230, v24, v25
	v_cvt_pk_bf16_f32 v231, v26, v27
	v_cvt_pk_bf16_f32 v232, v28, v29
	v_cvt_pk_bf16_f32 v233, v30, v31
	v_cvt_pk_bf16_f32 v234, v32, v33
	v_cvt_pk_bf16_f32 v235, v34, v35
	s_waitcnt lgkmcnt(3)
	v_mfma_f32_16x16x32_bf16 v[36:39], v[184:187], v[240:243], v[36:39]
	s_waitcnt lgkmcnt(2)
	v_mfma_f32_16x16x32_bf16 v[36:39], v[40:43], v[244:247], v[36:39]
	s_waitcnt lgkmcnt(1)
	v_mfma_f32_16x16x32_bf16 v[36:39], v[228:231], v[208:211], v[36:39]
	s_waitcnt lgkmcnt(0)
	v_mfma_f32_16x16x32_bf16 v[36:39], v[232:235], v[212:215], v[36:39]
	v_add_u32_e32 v227, v207, v155
	v_add_u32_e32 v216, s82, v142
	v_add3_u32 v217, s82, v155, v156
	v_mov_b32_e32 v44, 0
	v_mov_b32_e32 v45, 0
	v_mov_b32_e32 v46, 0
	v_mov_b32_e32 v47, 0
	s_and_saveexec_b64 s[14:15], s[46:47]
	ds_read_b128 v[44:47], v227 offset:14848
	s_or_b64 exec, exec, s[14:15]
	ds_read_b64 v[240:241], v216 offset:20992
	ds_read_b128 v[184:187], v217 offset:8704
	ds_read_b128 v[40:43], v217 offset:9472
	ds_read_b128 v[228:231], v217 offset:10240
	ds_read_b128 v[232:235], v217 offset:11008
	s_ashr_i32 s14, s32, 4
	s_add_i32 s14, s14, -2
	v_sub_u32_e32 v0, v51, v54
	v_cvt_pk_bf16_f32 v192, v36, v37
	v_cvt_pk_bf16_f32 v193, v38, v39
	v_mad_i32_i24 v0, v0, s14, v197
	global_store_dwordx2 v0, v[192:193], s[100:101]
	s_waitcnt lgkmcnt(4)
	v_mul_f32_dpp v4, v240, v4 row_newbcast:0 row_mask:0xf bank_mask:0xf
	v_mul_f32_dpp v5, v241, v5 row_newbcast:0 row_mask:0xf bank_mask:0xf
	v_mul_f32_dpp v6, v240, v6 row_newbcast:1 row_mask:0xf bank_mask:0xf
	v_mul_f32_dpp v7, v241, v7 row_newbcast:1 row_mask:0xf bank_mask:0xf
	v_mul_f32_dpp v8, v240, v8 row_newbcast:2 row_mask:0xf bank_mask:0xf
	v_mul_f32_dpp v9, v241, v9 row_newbcast:2 row_mask:0xf bank_mask:0xf
	v_mul_f32_dpp v10, v240, v10 row_newbcast:3 row_mask:0xf bank_mask:0xf
	v_mul_f32_dpp v11, v241, v11 row_newbcast:3 row_mask:0xf bank_mask:0xf
	s_waitcnt lgkmcnt(3)
	v_mfma_f32_16x16x32_bf16 v[4:7], v[184:187], v[44:47], v[4:7]
	ds_read_b128 v[184:187], v217 offset:11776
	v_mul_f32_dpp v12, v240, v12 row_newbcast:4 row_mask:0xf bank_mask:0xf
	v_mul_f32_dpp v13, v241, v13 row_newbcast:4 row_mask:0xf bank_mask:0xf
	v_mul_f32_dpp v14, v240, v14 row_newbcast:5 row_mask:0xf bank_mask:0xf
	v_mul_f32_dpp v15, v241, v15 row_newbcast:5 row_mask:0xf bank_mask:0xf
	s_waitcnt lgkmcnt(3)
	v_mfma_f32_16x16x32_bf16 v[8:11], v[40:43], v[44:47], v[8:11]
	ds_read_b128 v[40:43], v217 offset:12544
	v_mul_f32_dpp v16, v240, v16 row_newbcast:6 row_mask:0xf bank_mask:0xf
	v_mul_f32_dpp v17, v241, v17 row_newbcast:6 row_mask:0xf bank_mask:0xf
	v_mul_f32_dpp v18, v240, v18 row_newbcast:7 row_mask:0xf bank_mask:0xf
	v_mul_f32_dpp v19, v241, v19 row_newbcast:7 row_mask:0xf bank_mask:0xf
	s_waitcnt lgkmcnt(3)
	v_mfma_f32_16x16x32_bf16 v[12:15], v[228:231], v[44:47], v[12:15]
	ds_read_b128 v[228:231], v217 offset:13312
	v_mul_f32_dpp v20, v240, v20 row_newbcast:8 row_mask:0xf bank_mask:0xf
	v_mul_f32_dpp v21, v241, v21 row_newbcast:8 row_mask:0xf bank_mask:0xf
	v_mul_f32_dpp v22, v240, v22 row_newbcast:9 row_mask:0xf bank_mask:0xf
	v_mul_f32_dpp v23, v241, v23 row_newbcast:9 row_mask:0xf bank_mask:0xf
	s_waitcnt lgkmcnt(3)
	v_mfma_f32_16x16x32_bf16 v[16:19], v[232:235], v[44:47], v[16:19]
	ds_read_b128 v[232:235], v217 offset:14080
	v_mul_f32_dpp v24, v240, v24 row_newbcast:10 row_mask:0xf bank_mask:0xf
	v_mul_f32_dpp v25, v241, v25 row_newbcast:10 row_mask:0xf bank_mask:0xf
	v_mul_f32_dpp v26, v240, v26 row_newbcast:11 row_mask:0xf bank_mask:0xf
	v_mul_f32_dpp v27, v241, v27 row_newbcast:11 row_mask:0xf bank_mask:0xf
	s_waitcnt lgkmcnt(3)
	v_mfma_f32_16x16x32_bf16 v[20:23], v[184:187], v[44:47], v[20:23]
	v_mul_f32_dpp v28, v240, v28 row_newbcast:12 row_mask:0xf bank_mask:0xf
	v_mul_f32_dpp v29, v241, v29 row_newbcast:12 row_mask:0xf bank_mask:0xf
	v_mul_f32_dpp v30, v240, v30 row_newbcast:13 row_mask:0xf bank_mask:0xf
	v_mul_f32_dpp v31, v241, v31 row_newbcast:13 row_mask:0xf bank_mask:0xf
	s_waitcnt lgkmcnt(2)
	v_mfma_f32_16x16x32_bf16 v[24:27], v[40:43], v[44:47], v[24:27]
	v_mul_f32_dpp v32, v240, v32 row_newbcast:14 row_mask:0xf bank_mask:0xf
	v_mul_f32_dpp v33, v241, v33 row_newbcast:14 row_mask:0xf bank_mask:0xf
	v_mul_f32_dpp v34, v240, v34 row_newbcast:15 row_mask:0xf bank_mask:0xf
	v_mul_f32_dpp v35, v241, v35 row_newbcast:15 row_mask:0xf bank_mask:0xf
	s_waitcnt lgkmcnt(1)
	v_mfma_f32_16x16x32_bf16 v[28:31], v[228:231], v[44:47], v[28:31]
	s_waitcnt lgkmcnt(0)
	s_nop 0
	v_mfma_f32_16x16x32_bf16 v[32:35], v[232:235], v[44:47], v[32:35]
	v_add_u32_e32 v197, s32, v197
	v_add_u32_e32 v198, s32, v198
	v_add_u32_e32 v178, s32, v178
	v_add_u32_e32 v179, s32, v179
	v_lshl_add_u64 v[150:151], v[150:151], 0, v[146:147]
	s_add_i32 s81, s81, 1
	s_add_i32 s62, s62, 16
	s_add_i32 s14, s80, s81
	s_cmp_eq_u32 s14, 2
	s_barrier
	s_cbranch_scc1 .LBB0_1003
	s_branch .LBB0_979
.Lhl_alt_top:
	s_bitcmp1_b32 s81, 0
	s_cselect_b32 s82, 0x5800, 0
	v_lshlrev_b32_e32 v0, 1, v135
	v_lshlrev_b32_e32 v1, 1, v154
	v_add3_u32 v2, s82, v0, v1
	v_add_u32_e32 v207, s82, v63
	v_lshl_add_u32 v227, v54, 1, v207
	v_add_u32_e32 v0, v2, v176
	ds_read_b128 v[36:39], v2 offset:4352
	ds_read_b128 v[40:43], v2
	ds_read_b128 v[208:211], v2 offset:4416
	ds_read_b128 v[184:187], v2 offset:64
	ds_read_b128 v[212:215], v2 offset:4480
	ds_read_b128 v[228:231], v2 offset:128
	ds_read_b128 v[232:235], v2 offset:4544
	ds_read_b128 v[236:239], v2 offset:192
	ds_read_b64 v[188:189], v227 offset:14848
	ds_read2_b64 v[240:243], v0 offset1:4
	ds_read2_b64 v[244:247], v0 offset0:8 offset1:12
	s_and_b64 s[14:15], s[54:55], s[52:53]
	v_mov_b32_e32 v190, v3
	v_mov_b32_e32 v191, v3
	s_waitcnt lgkmcnt(9)
	v_mfma_f32_16x16x32_bf16 v[36:39], v[36:39], v[40:43], 0
	s_waitcnt lgkmcnt(7)
	v_mfma_f32_16x16x32_bf16 v[36:39], v[208:211], v[184:187], v[36:39]
	s_waitcnt lgkmcnt(5)
	v_mfma_f32_16x16x32_bf16 v[36:39], v[212:215], v[228:231], v[36:39]
	s_waitcnt lgkmcnt(3)
	v_mfma_f32_16x16x32_bf16 v[36:39], v[232:235], v[236:239], v[36:39]
	ds_read2_b64 v[208:211], v0 offset0:16 offset1:20
	ds_read2_b64 v[212:215], v0 offset0:24 offset1:28
	v_cvt_pk_bf16_f32 v184, v4, v5
	v_cvt_pk_bf16_f32 v185, v6, v7
	v_cvt_pk_bf16_f32 v186, v8, v9
	v_cvt_pk_bf16_f32 v187, v10, v11
	v_mov_b32_e32 v2, v3
	s_nop 0
	v_cndmask_b32_e64 v192, v38, 0, s[14:15]
	s_and_b64 s[14:15], s[14:15], s[50:51]
	v_cndmask_b32_e64 v0, v37, 0, s[14:15]
	s_and_b64 s[14:15], s[14:15], s[48:49]
	v_cndmask_b32_e64 v36, v36, 0, s[14:15]
	v_cndmask_b32_e64 v1, v39, 0, s[54:55]
	v_cvt_pk_bf16_f32 v0, v36, v0
	v_cvt_pk_bf16_f32 v1, v192, v1
	s_nop 0
	s_waitcnt lgkmcnt(4)
	v_mfma_f32_16x16x32_bf16 v[36:39], v[188:191], v[0:3], 0
	v_cvt_pk_bf16_f32 v40, v12, v13
	v_cvt_pk_bf16_f32 v41, v14, v15
	v_cvt_pk_bf16_f32 v42, v16, v17
	v_cvt_pk_bf16_f32 v43, v18, v19
	v_cvt_pk_bf16_f32 v228, v20, v21
	v_cvt_pk_bf16_f32 v229, v22, v23
	v_cvt_pk_bf16_f32 v230, v24, v25
	v_cvt_pk_bf16_f32 v231, v26, v27
	v_cvt_pk_bf16_f32 v232, v28, v29
	v_cvt_pk_bf16_f32 v233, v30, v31
	v_cvt_pk_bf16_f32 v234, v32, v33
	v_cvt_pk_bf16_f32 v235, v34, v35
	s_waitcnt lgkmcnt(3)
	v_mfma_f32_16x16x32_bf16 v[36:39], v[184:187], v[240:243], v[36:39]
	s_waitcnt lgkmcnt(2)
	v_mfma_f32_16x16x32_bf16 v[36:39], v[40:43], v[244:247], v[36:39]
	s_waitcnt lgkmcnt(1)
	v_mfma_f32_16x16x32_bf16 v[36:39], v[228:231], v[208:211], v[36:39]
	s_waitcnt lgkmcnt(0)
	v_mfma_f32_16x16x32_bf16 v[36:39], v[232:235], v[212:215], v[36:39]
	v_add_u32_e32 v227, v207, v155
	v_add_u32_e32 v216, s82, v142
	v_add3_u32 v217, s82, v155, v156
	v_mov_b32_e32 v44, 0
	v_mov_b32_e32 v45, 0
	v_mov_b32_e32 v46, 0
	v_mov_b32_e32 v47, 0
	s_and_saveexec_b64 s[14:15], s[46:47]
	ds_read_b128 v[44:47], v227 offset:14848
	s_or_b64 exec, exec, s[14:15]
	ds_read_b64 v[240:241], v216 offset:20992
	ds_read_b128 v[184:187], v217 offset:8704
	ds_read_b128 v[40:43], v217 offset:9472
	ds_read_b128 v[228:231], v217 offset:10240
	ds_read_b128 v[232:235], v217 offset:11008
	s_ashr_i32 s14, s32, 4
	s_add_i32 s14, s14, -2
	v_sub_u32_e32 v0, v51, v54
	v_cvt_pk_bf16_f32 v192, v36, v37
	v_cvt_pk_bf16_f32 v193, v38, v39
	v_mad_i32_i24 v0, v0, s14, v197
	global_store_dwordx2 v0, v[192:193], s[100:101]
	s_waitcnt lgkmcnt(4)
	v_mul_f32_dpp v4, v240, v4 row_newbcast:0 row_mask:0xf bank_mask:0xf
	v_mul_f32_dpp v5, v241, v5 row_newbcast:0 row_mask:0xf bank_mask:0xf
	v_mul_f32_dpp v6, v240, v6 row_newbcast:1 row_mask:0xf bank_mask:0xf
	v_mul_f32_dpp v7, v241, v7 row_newbcast:1 row_mask:0xf bank_mask:0xf
	v_mul_f32_dpp v8, v240, v8 row_newbcast:2 row_mask:0xf bank_mask:0xf
	v_mul_f32_dpp v9, v241, v9 row_newbcast:2 row_mask:0xf bank_mask:0xf
	v_mul_f32_dpp v10, v240, v10 row_newbcast:3 row_mask:0xf bank_mask:0xf
	v_mul_f32_dpp v11, v241, v11 row_newbcast:3 row_mask:0xf bank_mask:0xf
	s_waitcnt lgkmcnt(3)
	v_mfma_f32_16x16x32_bf16 v[4:7], v[184:187], v[44:47], v[4:7]
	ds_read_b128 v[184:187], v217 offset:11776
	v_mul_f32_dpp v12, v240, v12 row_newbcast:4 row_mask:0xf bank_mask:0xf
	v_mul_f32_dpp v13, v241, v13 row_newbcast:4 row_mask:0xf bank_mask:0xf
	v_mul_f32_dpp v14, v240, v14 row_newbcast:5 row_mask:0xf bank_mask:0xf
	v_mul_f32_dpp v15, v241, v15 row_newbcast:5 row_mask:0xf bank_mask:0xf
	s_waitcnt lgkmcnt(3)
	v_mfma_f32_16x16x32_bf16 v[8:11], v[40:43], v[44:47], v[8:11]
	ds_read_b128 v[40:43], v217 offset:12544
	v_mul_f32_dpp v16, v240, v16 row_newbcast:6 row_mask:0xf bank_mask:0xf
	v_mul_f32_dpp v17, v241, v17 row_newbcast:6 row_mask:0xf bank_mask:0xf
	v_mul_f32_dpp v18, v240, v18 row_newbcast:7 row_mask:0xf bank_mask:0xf
	v_mul_f32_dpp v19, v241, v19 row_newbcast:7 row_mask:0xf bank_mask:0xf
	s_waitcnt lgkmcnt(3)
	v_mfma_f32_16x16x32_bf16 v[12:15], v[228:231], v[44:47], v[12:15]
	ds_read_b128 v[228:231], v217 offset:13312
	v_mul_f32_dpp v20, v240, v20 row_newbcast:8 row_mask:0xf bank_mask:0xf
	v_mul_f32_dpp v21, v241, v21 row_newbcast:8 row_mask:0xf bank_mask:0xf
	v_mul_f32_dpp v22, v240, v22 row_newbcast:9 row_mask:0xf bank_mask:0xf
	v_mul_f32_dpp v23, v241, v23 row_newbcast:9 row_mask:0xf bank_mask:0xf
	s_waitcnt lgkmcnt(3)
	v_mfma_f32_16x16x32_bf16 v[16:19], v[232:235], v[44:47], v[16:19]
	ds_read_b128 v[232:235], v217 offset:14080
	v_mul_f32_dpp v24, v240, v24 row_newbcast:10 row_mask:0xf bank_mask:0xf
	v_mul_f32_dpp v25, v241, v25 row_newbcast:10 row_mask:0xf bank_mask:0xf
	v_mul_f32_dpp v26, v240, v26 row_newbcast:11 row_mask:0xf bank_mask:0xf
	v_mul_f32_dpp v27, v241, v27 row_newbcast:11 row_mask:0xf bank_mask:0xf
	s_waitcnt lgkmcnt(3)
	v_mfma_f32_16x16x32_bf16 v[20:23], v[184:187], v[44:47], v[20:23]
	v_mul_f32_dpp v28, v240, v28 row_newbcast:12 row_mask:0xf bank_mask:0xf
	v_mul_f32_dpp v29, v241, v29 row_newbcast:12 row_mask:0xf bank_mask:0xf
	v_mul_f32_dpp v30, v240, v30 row_newbcast:13 row_mask:0xf bank_mask:0xf
	v_mul_f32_dpp v31, v241, v31 row_newbcast:13 row_mask:0xf bank_mask:0xf
	s_waitcnt lgkmcnt(2)
	v_mfma_f32_16x16x32_bf16 v[24:27], v[40:43], v[44:47], v[24:27]
	v_mul_f32_dpp v32, v240, v32 row_newbcast:14 row_mask:0xf bank_mask:0xf
	v_mul_f32_dpp v33, v241, v33 row_newbcast:14 row_mask:0xf bank_mask:0xf
	v_mul_f32_dpp v34, v240, v34 row_newbcast:15 row_mask:0xf bank_mask:0xf
	v_mul_f32_dpp v35, v241, v35 row_newbcast:15 row_mask:0xf bank_mask:0xf
	s_waitcnt lgkmcnt(1)
	v_mfma_f32_16x16x32_bf16 v[28:31], v[228:231], v[44:47], v[28:31]
	s_waitcnt lgkmcnt(0)
	s_nop 0
	v_mfma_f32_16x16x32_bf16 v[32:35], v[232:235], v[44:47], v[32:35]
	s_add_i32 s14, s81, -1
	s_cmp_ge_u32 s14, s61
	s_cbranch_scc1 .Lhl_alt_tail
	s_cmp_ge_u32 s81, s61
	s_waitcnt vmcnt(1)
	v_mov_b32_e32 v199, v157
	v_mov_b32_e32 v200, v159
	v_mov_b32_e32 v201, v161
	v_mov_b32_e32 v202, v163
	v_mov_b32_e32 v203, v166
	v_mov_b32_e32 v204, v167
	v_mov_b32_e32 v205, v168
	v_mov_b32_e32 v206, v169
	v_mov_b64_e32 v[148:149], v[164:165]
	s_cbranch_scc1 .Lhl_alt_982
	global_load_ushort v168, v197, s[12:13]
	global_load_ushort v169, v197, s[98:99]
	global_load_ushort v166, v198, s[12:13]
	global_load_ushort v167, v198, s[98:99]
	global_load_ushort v161, v178, s[12:13]
	global_load_ushort v163, v178, s[98:99]
	global_load_ushort v157, v179, s[12:13]
	global_load_ushort v159, v179, s[98:99]
	global_load_dwordx2 v[164:165], v[150:151], off
